# strategy 4 refined: priority back to 0 for sample-group attention items (their waves 4-7 are loaders), on top of v024
# speedup vs baseline: 1.0106x; 1.0004x over previous
; __device__ __forceinline__ void attn_item(const P& p, Frame& F, const bool is_s, const int b, const int g, const int c) {
;     ...
;     const int hh = F.wave & 3, qh = F.wave >> 2, ql = F.lane & 31, half = F.lane >> 5, h = 4 * g + hh, iq = 32 * qh + ql;
;     const bool qvalid = is_s ? (qh == 0 && ql < 4) : true;
;     const int t = is_s ? PAST + ql : 64 * c + iq;
;     const int mrow = is_s ? (qvalid ? MP + b * 4 + ql : MP) : b * TP + t;
;     const int item8 = (is_s ? 512 + b * 2 + g : (b * 2 + g) * 32 + c) * 8;
; template <int LO, int HI> __global__ void __launch_bounds__(NTHR, 2) mega(P p) {
;     ...
;               if (k < 2 * NATT) { if (k & 1) ic = k >> 1; else ia = k >> 1; } else ic = k - NATT;
;               if (ic >= 0) { tr_late_batch(p, F, ic); continue; }
;               const bool is_s = ia < 64; const int kk = is_s ? ia : ia - 64;
;               attn_item(p, F, is_s, is_s ? kk >> 1 : (kk & 15) >> 1, kk & 1, is_s ? 0 : 31 - (kk >> 4)); } }
.LBB0_1872:
	s_sub_i32 s2, s10, 64
	s_cmp_lt_i32 s10, 64
	s_cselect_b64 s[0:1], -1, 0
	s_and_b64 s[0:1], s[0:1], exec
	s_cselect_b32 s5, s10, s2
	s_ashr_i32 s2, s5, 4
	s_sub_i32 s3, 31, s2
	s_cmp_lt_i32 s10, 64
	s_cselect_b64 s[8:9], -1, 0
	s_cbranch_scc0 .Lprio_smp_done
	s_setprio 0
.Lprio_smp_done:
	v_writelane_b32 v252, s90, 43
	s_and_b64 s[0:1], s[8:9], exec
	v_mov_b32_e32 v226, v0
	s_cselect_b32 s4, 0, s3
	s_cmp_gt_i32 s10, 63
	v_readlane_b32 s0, v252, 25
	v_and_b32_e32 v227, 31, v226
	s_cselect_b64 s[56:57], -1, 0
	v_or_b32_e32 v1, s0, v227
	s_lshl_b32 s6, s4, 6
	s_mov_b32 s91, s3
	s_bfe_u32 s3, s5, 0x30001
	v_cmp_gt_u32_e64 s[0:1], 4, v227
	v_writelane_b32 v252, s6, 44
	v_add_u32_e32 v228, s6, v1
	s_mov_b64 s[6:7], -1
	s_and_b64 vcc, exec, s[56:57]
	s_cbranch_vccz .LBB0_1874
	v_lshl_add_u32 v4, s3, 11, v228
	s_mov_b64 s[6:7], 0
